# v45 + prompt attention: second batch of V^T LDS reads hoisted, cross-half row max via v_permlane32_swap instead of ds_bpermute
# baseline (speedup 1.0000x reference)
; #define LAS __attribute__((address_space(3)))
; __device__ __forceinline__ unsigned cvtpk(float lo, float hi) { f32x2_t v = {lo, hi}; bf16x2_t b = __builtin_convertvector(v, bf16x2_t); return __builtin_bit_cast(unsigned, b); }
; __device__ __forceinline__ s16x4 vtr(const LAS unsigned char* p) { return __builtin_bit_cast(s16x4, __builtin_amdgcn_ds_read_tr16_b64_v4i16((LAS s16x4*)p)); }
; #define MFMA32(a, b, c) __builtin_amdgcn_mfma_f32_32x32x16_bf16((a), (b), (c), 0, 0, 0)
; __device__ __forceinline__ void attn_mfma_phase(LAS unsigned char* lds, const bf16* QKVb, bf16* OPART, float2* ML, int tid, int wave, int lane) {
;     ...
;             for (int e = 0; e < 16; ++e) tm = fmaxf(tm, s[e]);
;             tm = fmaxf(tm, __shfl_xor(tm, 32));
;             const float mn = fmaxf(m, tm), scl = __builtin_amdgcn_exp2f(m - mn);
;             m = mn; l *= scl;
;             if (__builtin_amdgcn_ballot_w64(scl != 1.0f)) {
; #pragma unroll
;                 for (int e = 0; e < 16; ++e) { o0[e] *= scl; o1[e] *= scl; }
;             }
;             float psum = 0.f;
; #pragma unroll
;             for (int e = 0; e < 16; ++e) { s[e] = __builtin_amdgcn_exp2f(s[e] - mn); psum += s[e]; }
;             l += psum;
;             v4u pw0, pw1;
;             pw0.x = cvtpk(s[0], s[1]); pw0.y = cvtpk(s[2], s[3]); pw0.z = cvtpk(s[4], s[5]); pw0.w = cvtpk(s[6], s[7]);
;             pw1.x = cvtpk(s[8], s[9]); pw1.y = cvtpk(s[10], s[11]); pw1.z = cvtpk(s[12], s[13]); pw1.w = cvtpk(s[14], s[15]);
;             const bf16x8 pf0 = __builtin_bit_cast(bf16x8, pw0), pf1 = __builtin_bit_cast(bf16x8, pw1);
; #pragma unroll
;             for (int st = 0; st < 2; ++st) {
;                 const LAS unsigned char* a0 = vimg + (jb + 16 * st + 4 * hh + tq) * RSV + (16 * blk + 4 * tp) * 2;
;                 const s16x4 lo0 = vtr(a0), hi0 = vtr(a0 + 8 * RSV), lo1 = vtr(a0 + 64), hi1 = vtr(a0 + 8 * RSV + 64);
;                 const bf16x8 v0 = __builtin_shufflevector(lo0, hi0, 0, 1, 2, 3, 4, 5, 6, 7), v1 = __builtin_shufflevector(lo1, hi1, 0, 1, 2, 3, 4, 5, 6, 7);
;                 o0 = MFMA32(v0, st == 0 ? pf0 : pf1, o0);
;                 o1 = MFMA32(v1, st == 0 ? pf0 : pf1, o1);
;             }
;         }
.LBB0_1047:
	s_mov_b32 s33, 0xf149f2ca
	s_nop 7
	v_max3_f32 v50, v34, s33, v35
	v_max3_f32 v50, v50, v36, v37
	v_max3_f32 v50, v50, v38, v39
	v_max3_f32 v50, v50, v40, v41
	v_max3_f32 v50, v50, v42, v43
	v_max3_f32 v50, v50, v44, v45
	v_max3_f32 v50, v50, v46, v47
	v_max3_f32 v50, v50, v48, v49
	v_mov_b32_e32 v51, v50
	s_nop 1
	v_permlane32_swap_b32_e32 v51, v50
	s_nop 0
	v_max3_f32 v50, v177, v50, v51
	v_sub_f32_e32 v51, v177, v50
	v_exp_f32_e32 v52, v51
	s_nop 0
	v_cmp_neq_f32_e32 vcc, 1.0, v52
	s_cbranch_vccz .LBB0_1049
	v_pk_mul_f32 v[16:17], v[16:17], v[52:53] op_sel_hi:[1,0]
	v_pk_mul_f32 v[14:15], v[14:15], v[52:53] op_sel_hi:[1,0]
	v_pk_mul_f32 v[12:13], v[12:13], v[52:53] op_sel_hi:[1,0]
	v_pk_mul_f32 v[10:11], v[10:11], v[52:53] op_sel_hi:[1,0]
	v_pk_mul_f32 v[8:9], v[8:9], v[52:53] op_sel_hi:[1,0]
	v_pk_mul_f32 v[6:7], v[6:7], v[52:53] op_sel_hi:[1,0]
	v_pk_mul_f32 v[4:5], v[4:5], v[52:53] op_sel_hi:[1,0]
	v_pk_mul_f32 v[2:3], v[2:3], v[52:53] op_sel_hi:[1,0]
	v_pk_mul_f32 v[32:33], v[32:33], v[52:53] op_sel_hi:[1,0]
	v_pk_mul_f32 v[30:31], v[30:31], v[52:53] op_sel_hi:[1,0]
	v_pk_mul_f32 v[28:29], v[28:29], v[52:53] op_sel_hi:[1,0]
	v_pk_mul_f32 v[26:27], v[26:27], v[52:53] op_sel_hi:[1,0]
	v_pk_mul_f32 v[24:25], v[24:25], v[52:53] op_sel_hi:[1,0]
	v_pk_mul_f32 v[22:23], v[22:23], v[52:53] op_sel_hi:[1,0]
	v_pk_mul_f32 v[20:21], v[20:21], v[52:53] op_sel_hi:[1,0]
	v_pk_mul_f32 v[18:19], v[18:19], v[52:53] op_sel_hi:[1,0]
.LBB0_1049:
	v_sub_f32_e32 v34, v34, v50
	v_exp_f32_e32 v51, v34
	v_sub_f32_e32 v35, v35, v50
	v_exp_f32_e32 v35, v35
	v_sub_f32_e32 v36, v36, v50
	v_exp_f32_e32 v53, v36
	v_sub_f32_e32 v36, v37, v50
	v_exp_f32_e32 v37, v36
	v_sub_f32_e32 v36, v38, v50
	v_add_f32_e32 v34, 0, v51
	v_exp_f32_e32 v38, v36
	v_sub_f32_e32 v36, v39, v50
	v_add_f32_e32 v34, v35, v34
	v_exp_f32_e32 v39, v36
	v_sub_f32_e32 v36, v40, v50
	v_add_f32_e32 v34, v53, v34
	v_exp_f32_e32 v40, v36
	v_sub_f32_e32 v36, v41, v50
	v_add_f32_e32 v34, v37, v34
	v_exp_f32_e32 v41, v36
	v_sub_f32_e32 v36, v42, v50
	v_add_f32_e32 v34, v38, v34
	v_exp_f32_e32 v42, v36
	v_sub_f32_e32 v36, v43, v50
	v_add_f32_e32 v34, v39, v34
	v_exp_f32_e32 v43, v36
	v_sub_f32_e32 v36, v44, v50
	v_add_f32_e32 v34, v40, v34
	v_exp_f32_e32 v44, v36
	v_sub_f32_e32 v36, v45, v50
	v_add_f32_e32 v34, v41, v34
	v_exp_f32_e32 v45, v36
	v_sub_f32_e32 v36, v46, v50
	v_add_f32_e32 v34, v42, v34
	v_exp_f32_e32 v46, v36
	v_sub_f32_e32 v36, v47, v50
	v_add_f32_e32 v34, v43, v34
	v_exp_f32_e32 v47, v36
	v_add_f32_e32 v34, v44, v34
	v_sub_f32_e32 v36, v48, v50
	v_add_f32_e32 v34, v45, v34
	v_exp_f32_e32 v48, v36
	v_sub_f32_e32 v36, v49, v50
	v_add_f32_e32 v34, v46, v34
	v_exp_f32_e32 v49, v36
	v_cvt_pk_bf16_f32 v36, v51, v35
	v_add_u32_e32 v35, 0, v147
	v_add_f32_e32 v34, v47, v34
	v_cvt_pk_bf16_f32 v38, v38, v39
	v_cvt_pk_bf16_f32 v39, v40, v41
	v_cvt_pk_bf16_f32 v40, v42, v43
	v_cvt_pk_bf16_f32 v41, v44, v45
	v_cvt_pk_bf16_f32 v42, v46, v47
	ds_read_b64_tr_b16 v[44:45], v35 offset:55296
	ds_read_b64_tr_b16 v[46:47], v35 offset:56832
	ds_read_b64_tr_b16 v[54:55], v35 offset:55360
	ds_read_b64_tr_b16 v[56:57], v35 offset:56896
	ds_read_b64_tr_b16 v[58:59], v35 offset:58368
	ds_read_b64_tr_b16 v[60:61], v35 offset:59904
	ds_read_b64_tr_b16 v[62:63], v35 offset:58432
	ds_read_b64_tr_b16 v[64:65], v35 offset:59968
	v_cvt_pk_bf16_f32 v37, v53, v37
	v_cvt_pk_bf16_f32 v43, v48, v49
	v_add_f32_e32 v34, v48, v34
	s_waitcnt lgkmcnt(6)
	v_mfma_f32_32x32x16_bf16 v[2:17], v[44:47], v[36:39], v[2:17]
	v_add_f32_e32 v34, v49, v34
	s_add_i32 s33, s87, 1
	v_fmac_f32_e32 v34, v176, v52
	v_add_u32_e32 v147, 0x1800, v147
	v_add_u32_e32 v175, 0x1200, v175
	s_cmp_gt_i32 s87, 3
	s_waitcnt lgkmcnt(4)
	v_mfma_f32_32x32x16_bf16 v[18:33], v[54:57], v[36:39], v[18:33]
	s_waitcnt lgkmcnt(2)
	v_mfma_f32_32x32x16_bf16 v[2:17], v[58:61], v[40:43], v[2:17]
	s_waitcnt lgkmcnt(0)
	v_mfma_f32_32x32x16_bf16 v[18:33], v[62:65], v[40:43], v[18:33]
	s_cbranch_scc1 .LBB0_1052
	v_mov_b32_e32 v176, v34
	v_mov_b32_e32 v177, v50
	s_mov_b32 s87, s33
	s_branch .LBB0_1041
